# in_proj tile order: every workgroup gets exactly one scattered-store V tile
# baseline (speedup 1.0000x reference)
.LBB0_122:
	v_readlane_b32 s12, v253, 2
	s_add_i32 s68, s68, 1
	v_readlane_b32 s13, v253, 3
	s_mul_i32 s3, s68, s13
	s_mul_hi_u32 s5, s68, s12
	s_add_i32 s5, s5, s3
	s_mul_i32 s3, s68, s12
	v_readlane_b32 s14, v254, 5
	s_add_u32 s12, s3, s94
	v_readlane_b32 s15, v254, 6
	s_addc_u32 s13, s5, s15
	v_readlane_b32 s3, v253, 2
	s_nop 0
	s_cmp_eq_u32 s3, 0x100
	s_cselect_b32 s3, 0x80, 0
	s_cmp_gt_u32 s68, 2
	s_cselect_b32 s3, s3, 0
	s_xor_b32 s12, s12, s3
	v_cmp_gt_i64_e64 s[40:41], s[12:13], v[142:143]
	s_and_b64 vcc, exec, s[40:41]
	s_cbranch_vccnz .LBB0_124
	s_ashr_i32 s3, s12, 31
	s_lshr_b32 s3, s3, 29
	s_add_i32 s3, s12, s3
	s_ashr_i32 s5, s3, 3
	s_and_b32 s3, s3, -8
	s_sub_i32 s3, s12, s3
	s_cmp_lt_i32 s3, 0
	s_movk_i32 s10, 0xc1
	s_cselect_b32 s10, s10, 0xc0
	s_mul_i32 s3, s3, s10
	s_add_i32 s3, s3, s5
	s_mul_hi_i32 s5, s3, 0x2aaaaaab
	s_lshr_b32 s10, s5, 31
	s_ashr_i32 s5, s5, 4
	s_add_i32 s5, s5, s10
	s_lshl_b32 s10, s5, 3
	s_sub_i32 s14, 0x80, s10
	s_min_i32 s14, s14, 8
	s_abs_i32 s15, s14
	v_cvt_f32_u32_e32 v0, s15
	s_sub_i32 s17, 0, s15
	s_mulk_i32 s5, 0x60
	s_sub_i32 s3, s3, s5
	v_rcp_iflag_f32_e32 v0, v0
	s_abs_i32 s5, s3
	s_xor_b32 s16, s3, s14
	s_ashr_i32 s16, s16, 31
	v_mul_f32_e32 v0, 0x4f7ffffe, v0
	v_cvt_u32_f32_e32 v0, v0
	s_nop 0
	v_readfirstlane_b32 s18, v0
	s_mul_i32 s17, s17, s18
	s_mul_hi_u32 s17, s18, s17
	s_add_i32 s18, s18, s17
	s_mul_hi_u32 s17, s5, s18
	s_mul_i32 s18, s17, s15
	s_sub_i32 s5, s5, s18
	s_add_i32 s19, s17, 1
	s_sub_i32 s18, s5, s15
	s_cmp_ge_u32 s5, s15
	s_cselect_b32 s17, s19, s17
	s_cselect_b32 s5, s18, s5
	s_add_i32 s18, s17, 1
	s_cmp_ge_u32 s5, s15
	s_cselect_b32 s5, s18, s17
	s_xor_b32 s5, s5, s16
	s_sub_i32 s38, s5, s16
	s_mul_i32 s5, s38, s14
	s_sub_i32 s3, s3, s5
	s_add_i32 s66, s10, s3
